# M17 + poolfold (P0) Bt staging: 8 serialized cold loads issued together
# speedup vs baseline: 1.0046x; 1.0004x over previous
.LBB0_57:
	s_and_b64 vcc, exec, s[6:7]
	s_cbranch_vccz .LBB0_22
	s_lshl_b32 s4, s56, 2
	s_and_b32 s6, s4, 0xffffff80
	s_lshl_b32 s3, s56, 6
	s_ashr_i32 s7, s6, 31
	s_and_b32 s3, s3, 0x7c0
	s_lshl_b64 s[12:13], s[6:7], 2
	s_add_u32 s12, s22, s12
	s_addc_u32 s13, s23, s13
	v_add_u32_e32 v30, s3, v37
	v_mov_b64_e32 v[32:33], s[12:13]
	v_ashrrev_i32_e32 v31, 31, v30
	v_mad_i64_i32 v[2:3], s[12:13], v30, s62, v[32:33]
	v_lshl_add_u64 v[2:3], v[2:3], 0, v[114:115]
	v_lshl_add_u64 v[30:31], v[30:31], 2, s[24:25]
	global_load_dwordx4 v[2:5], v[2:3], off nt
	v_mov_b32_e32 v46, 0
	global_load_dword v30, v[30:31], off
	s_mov_b32 s4, -4
	v_mov_b32_e32 v93, v88
	v_mov_b32_e32 v94, v92
	v_mov_b32_e32 v47, v46
	v_mov_b32_e32 v40, v46
	v_mov_b32_e32 v38, v46
	v_mov_b32_e32 v41, v46
	v_mov_b32_e32 v39, v46
	v_mov_b32_e32 v44, v46
	v_mov_b32_e32 v42, v46
	v_mov_b32_e32 v45, v46
	v_mov_b32_e32 v43, v46
	v_mov_b32_e32 v48, v46
	v_mov_b32_e32 v49, v46
	s_waitcnt vmcnt(0)
	v_pk_mul_f32 v[2:3], v[2:3], v[30:31] op_sel_hi:[1,0]
	v_pk_mul_f32 v[4:5], v[4:5], v[30:31] op_sel_hi:[1,0]
	v_add_u32_e32 v30, s3, v68
	ds_write_b128 v76, v[2:5]
	v_ashrrev_i32_e32 v31, 31, v30
	v_mad_i64_i32 v[2:3], s[12:13], v30, s62, v[32:33]
	v_lshl_add_u64 v[2:3], v[2:3], 0, v[114:115]
	v_lshl_add_u64 v[30:31], v[30:31], 2, s[24:25]
	global_load_dwordx4 v[2:5], v[2:3], off nt
	s_nop 0
	global_load_dword v30, v[30:31], off
	s_waitcnt vmcnt(0)
	v_pk_mul_f32 v[2:3], v[2:3], v[30:31] op_sel_hi:[1,0]
	v_pk_mul_f32 v[4:5], v[4:5], v[30:31] op_sel_hi:[1,0]
	v_add_u32_e32 v30, s3, v69
	ds_write_b128 v77, v[2:5]
	v_ashrrev_i32_e32 v31, 31, v30
	v_mad_i64_i32 v[2:3], s[12:13], v30, s62, v[32:33]
	v_lshl_add_u64 v[2:3], v[2:3], 0, v[114:115]
	v_lshl_add_u64 v[30:31], v[30:31], 2, s[24:25]
	global_load_dwordx4 v[2:5], v[2:3], off nt
	s_nop 0
	global_load_dword v30, v[30:31], off
	s_waitcnt vmcnt(0)
	v_pk_mul_f32 v[2:3], v[2:3], v[30:31] op_sel_hi:[1,0]
	v_pk_mul_f32 v[4:5], v[4:5], v[30:31] op_sel_hi:[1,0]
	v_add_u32_e32 v30, s3, v70
	ds_write_b128 v78, v[2:5]
	v_ashrrev_i32_e32 v31, 31, v30
	v_mad_i64_i32 v[2:3], s[12:13], v30, s62, v[32:33]
	v_lshl_add_u64 v[2:3], v[2:3], 0, v[114:115]
	v_lshl_add_u64 v[30:31], v[30:31], 2, s[24:25]
	global_load_dwordx4 v[2:5], v[2:3], off nt
	v_mov_b32_e32 v32, v46
	global_load_dword v30, v[30:31], off
	v_mov_b32_e32 v33, v46
	s_waitcnt vmcnt(0)
	v_pk_mul_f32 v[2:3], v[2:3], v[30:31] op_sel_hi:[1,0]
	v_pk_mul_f32 v[4:5], v[4:5], v[30:31] op_sel_hi:[1,0]
	ds_write_b128 v79, v[2:5]
	v_add_u32_e32 v134, s6, v37
	v_ashrrev_i32_e32 v135, 31, v134
	v_lshlrev_b64 v[134:135], 9, v[134:135]
	v_lshl_add_u64 v[134:135], v[14:15], 0, v[134:135]
	global_load_dwordx4 v[96:99], v[134:135], off nt
	v_add_u32_e32 v134, s6, v68
	v_ashrrev_i32_e32 v135, 31, v134
	v_lshlrev_b64 v[134:135], 9, v[134:135]
	v_lshl_add_u64 v[134:135], v[14:15], 0, v[134:135]
	global_load_dwordx4 v[100:103], v[134:135], off nt
	v_add_u32_e32 v134, s6, v69
	v_ashrrev_i32_e32 v135, 31, v134
	v_lshlrev_b64 v[134:135], 9, v[134:135]
	v_lshl_add_u64 v[134:135], v[14:15], 0, v[134:135]
	global_load_dwordx4 v[104:107], v[134:135], off nt
	v_add_u32_e32 v134, s6, v70
	v_ashrrev_i32_e32 v135, 31, v134
	v_lshlrev_b64 v[134:135], 9, v[134:135]
	v_lshl_add_u64 v[134:135], v[14:15], 0, v[134:135]
	global_load_dwordx4 v[108:111], v[134:135], off nt
	v_add_u32_e32 v134, s6, v71
	v_ashrrev_i32_e32 v135, 31, v134
	v_lshlrev_b64 v[134:135], 9, v[134:135]
	v_lshl_add_u64 v[134:135], v[14:15], 0, v[134:135]
	global_load_dwordx4 v[118:121], v[134:135], off nt
	v_add_u32_e32 v134, s6, v72
	v_ashrrev_i32_e32 v135, 31, v134
	v_lshlrev_b64 v[134:135], 9, v[134:135]
	v_lshl_add_u64 v[134:135], v[14:15], 0, v[134:135]
	global_load_dwordx4 v[122:125], v[134:135], off nt
	v_add_u32_e32 v134, s6, v73
	v_ashrrev_i32_e32 v135, 31, v134
	v_lshlrev_b64 v[134:135], 9, v[134:135]
	v_lshl_add_u64 v[134:135], v[14:15], 0, v[134:135]
	global_load_dwordx4 v[126:129], v[134:135], off nt
	v_add_u32_e32 v134, s6, v74
	v_ashrrev_i32_e32 v135, 31, v134
	v_lshlrev_b64 v[134:135], 9, v[134:135]
	v_lshl_add_u64 v[134:135], v[14:15], 0, v[134:135]
	global_load_dwordx4 v[130:133], v[134:135], off nt
	v_mov_b32_e32 v30, v46
	v_mov_b32_e32 v31, v46
	s_waitcnt vmcnt(7)
	ds_write_b128 v76, v[96:99] offset:32768
	s_waitcnt vmcnt(6)
	ds_write_b128 v77, v[100:103] offset:32768
	s_waitcnt vmcnt(5)
	ds_write_b128 v78, v[104:107] offset:32768
	s_waitcnt vmcnt(4)
	ds_write_b128 v79, v[108:111] offset:32768
	s_waitcnt vmcnt(3)
	ds_write_b128 v80, v[118:121] offset:32768
	s_waitcnt vmcnt(2)
	ds_write_b128 v81, v[122:125] offset:32768
	s_waitcnt vmcnt(1)
	ds_write_b128 v82, v[126:129] offset:32768
	s_waitcnt vmcnt(0)
	ds_write_b128 v83, v[130:133] offset:32768
	s_waitcnt lgkmcnt(0)
	s_barrier
